# P2 wave units remapped so the eight waves of a workgroup cover the eight heads of one token block (on top of the combined version)
# baseline (speedup 1.0000x reference)
; __device__ __forceinline__ void p2_wave_unit(int u, const bf16_t* H, float* kmean, unsigned* ctl, int lane) {
;     const int isn = u >> 10; u &= 1023; const int bh = u >> 6, blk = u & 63, b = bh >> 3, h = bh & 7, rs = lane >> 3, ch = lane & 7;
;     const bf16_t* base = H + ((size_t)b * SEQ + blk * 256 + rs) * HQ + h * 64 + ch * 8;
.LBB0_196:
	s_and_b32 s100, s3, 0x600
	s_and_b32 s101, s3, 7
	s_lshl_b32 s101, s101, 6
	s_or_b32 s100, s100, s101
	s_bfe_u32 s101, s3, 0x60003
	s_or_b32 s100, s100, s101
	s_lshl_b32 s4, s100, 1
	s_and_b32 s30, s4, 0x380
	s_lshl_b32 s4, s100, 5
	s_lshl_b32 s5, s100, 8
	s_and_b32 s4, s4, 0x4000
	s_and_b32 s5, s5, 0x3f00
	s_or_b32 s4, s5, s4
	v_or_b32_e32 v0, s4, v22
	v_mul_u32_u24_e32 v0, 0x1500, v0
	s_mov_b64 s[18:19], -1
	s_cmpk_lt_u32 s3, 0x400
	v_lshlrev_b32_e32 v0, 1, v0
	s_cbranch_scc1 .LBB0_209
	s_waitcnt lgkmcnt(0)
	v_lshl_add_u64 v[6:7], s[30:31], 0, v[0:1]
	s_bfe_u32 s4, s100, 0x40006
	v_lshl_add_u64 v[6:7], v[4:5], 0, v[6:7]
	v_mov_b32_e32 v10, 0
	s_mov_b64 s[18:19], 0
	v_mov_b32_e32 v11, 0

; __device__ __forceinline__ float bf_lo(unsigned w) { return __uint_as_float(w << 16); }
; __device__ __forceinline__ float bf_hi(unsigned w) { return __uint_as_float(w & 0xffff0000u); }
; __device__ __forceinline__ void p2_wave_unit(int u, const bf16_t* H, float* kmean, unsigned* ctl, int lane) {
;     ...
;         float s[8] = {0.f, 0.f, 0.f, 0.f, 0.f, 0.f, 0.f, 0.f};
; #pragma unroll 4
;         for (int it = 0; it < 32; ++it) { const u32x4 w = *(const u32x4*)(base + (size_t)it * 8 * HQ + C_MK);
;             s[0] += bf_lo(w.x); s[1] += bf_hi(w.x); s[2] += bf_lo(w.y); s[3] += bf_hi(w.y); s[4] += bf_lo(w.z); s[5] += bf_hi(w.z); s[6] += bf_lo(w.w); s[7] += bf_hi(w.w); }
; #pragma unroll
;         for (int i = 0; i < 8; ++i) { s[i] += __shfl_xor(s[i], 8); s[i] += __shfl_xor(s[i], 16); s[i] += __shfl_xor(s[i], 32); }
;         if (rs == 0) { float* d = kmean + ((size_t)bh * 64 + blk) * 64 + ch * 8; f32x4 o0 = {s[0], s[1], s[2], s[3]}, o1 = {s[4], s[5], s[6], s[7]}; *(f32x4*)d = o0 * (1.f / 256.f); *(f32x4*)(d + 4) = o1 * (1.f / 256.f); }
.LBB0_211:
	v_lshl_add_u64 v[16:17], v[6:7], 0, s[18:19]
	s_waitcnt vmcnt(0)
	s_mov_b64 s[98:99], 0x20801000
	v_lshl_add_u64 v[70:71], v[16:17], 0, s[98:99]
	global_load_dwordx4 v[54:57], v[70:71], off offset:3584
	s_mov_b64 s[98:99], 0x20816000
	v_lshl_add_u64 v[70:71], v[16:17], 0, s[98:99]
	global_load_dwordx4 v[58:61], v[70:71], off offset:3584
	s_mov_b64 s[98:99], 0x2082b000
	v_lshl_add_u64 v[70:71], v[16:17], 0, s[98:99]
	global_load_dwordx4 v[62:65], v[70:71], off offset:3584
	s_mov_b64 s[98:99], 0x20840000
	v_lshl_add_u64 v[70:71], v[16:17], 0, s[98:99]
	global_load_dwordx4 v[66:69], v[70:71], off offset:3584
	v_add_co_u32_e32 v18, vcc, 0x20801000, v16
	s_mov_b32 s4, 0x20816000
	s_nop 0
	v_addc_co_u32_e32 v19, vcc, 0, v17, vcc
	s_add_u32 s18, s18, 0x54000
	s_addc_u32 s19, s19, 0
	s_cmp_eq_u32 s18, 0x2a0000
	s_waitcnt vmcnt(3)
	v_mov_b32_e32 v18, v54
	v_mov_b32_e32 v19, v55
	v_mov_b32_e32 v20, v56
	v_mov_b32_e32 v21, v57
	v_lshlrev_b32_e32 v24, 16, v18
	v_and_b32_e32 v25, 0xffff0000, v18
	v_lshlrev_b32_e32 v18, 16, v19
	v_and_b32_e32 v19, 0xffff0000, v19
	v_pk_add_f32 v[12:13], v[12:13], v[18:19]
	v_lshlrev_b32_e32 v18, 16, v20
	v_and_b32_e32 v19, 0xffff0000, v20
	v_pk_add_f32 v[18:19], v[10:11], v[18:19]
	v_lshlrev_b32_e32 v10, 16, v21
	v_and_b32_e32 v11, 0xffff0000, v21
	v_pk_add_f32 v[20:21], v[8:9], v[10:11]
	v_add_co_u32_e32 v8, vcc, s4, v16
	v_pk_add_f32 v[14:15], v[14:15], v[24:25]
	s_nop 0
	v_addc_co_u32_e32 v9, vcc, 0, v17, vcc
	s_mov_b32 s4, 0x2082b000
	s_waitcnt vmcnt(2)
	v_mov_b32_e32 v8, v58
	v_mov_b32_e32 v9, v59
	v_mov_b32_e32 v10, v60
	v_mov_b32_e32 v11, v61
	v_lshlrev_b32_e32 v24, 16, v8
	v_and_b32_e32 v25, 0xffff0000, v8
	v_lshlrev_b32_e32 v8, 16, v9
	v_and_b32_e32 v9, 0xffff0000, v9
	v_pk_add_f32 v[12:13], v[12:13], v[8:9]
	v_lshlrev_b32_e32 v8, 16, v10
	v_and_b32_e32 v9, 0xffff0000, v10
	v_pk_add_f32 v[18:19], v[18:19], v[8:9]
	v_lshlrev_b32_e32 v8, 16, v11
	v_and_b32_e32 v9, 0xffff0000, v11
	v_pk_add_f32 v[20:21], v[20:21], v[8:9]
	v_add_co_u32_e32 v8, vcc, s4, v16
	v_pk_add_f32 v[14:15], v[14:15], v[24:25]
	s_nop 0
	v_addc_co_u32_e32 v9, vcc, 0, v17, vcc
	s_mov_b32 s4, 0x20840000
	s_waitcnt vmcnt(1)
	v_mov_b32_e32 v8, v62
	v_mov_b32_e32 v9, v63
	v_mov_b32_e32 v10, v64
	v_mov_b32_e32 v11, v65
	v_lshlrev_b32_e32 v24, 16, v8
	v_and_b32_e32 v25, 0xffff0000, v8
	v_lshlrev_b32_e32 v8, 16, v9
	v_and_b32_e32 v9, 0xffff0000, v9
	v_pk_add_f32 v[8:9], v[12:13], v[8:9]
	v_lshlrev_b32_e32 v12, 16, v10
	v_and_b32_e32 v13, 0xffff0000, v10
	v_lshlrev_b32_e32 v10, 16, v11
	v_and_b32_e32 v11, 0xffff0000, v11
	v_pk_add_f32 v[20:21], v[20:21], v[10:11]
	v_add_co_u32_e32 v10, vcc, s4, v16
	v_pk_add_f32 v[14:15], v[14:15], v[24:25]
	s_nop 0
	v_addc_co_u32_e32 v11, vcc, 0, v17, vcc
	v_pk_add_f32 v[24:25], v[18:19], v[12:13]
	s_waitcnt vmcnt(0)
	v_mov_b32_e32 v16, v66
	v_mov_b32_e32 v17, v67
	v_mov_b32_e32 v18, v68
	v_mov_b32_e32 v19, v69
	v_lshlrev_b32_e32 v10, 16, v16
	v_and_b32_e32 v11, 0xffff0000, v16
	v_pk_add_f32 v[14:15], v[14:15], v[10:11]
	v_lshlrev_b32_e32 v10, 16, v17
	v_and_b32_e32 v11, 0xffff0000, v17
	v_pk_add_f32 v[12:13], v[8:9], v[10:11]
	v_lshlrev_b32_e32 v8, 16, v18
	v_and_b32_e32 v9, 0xffff0000, v18
	v_pk_add_f32 v[10:11], v[24:25], v[8:9]
	v_lshlrev_b32_e32 v8, 16, v19
	v_and_b32_e32 v9, 0xffff0000, v19
	v_pk_add_f32 v[8:9], v[20:21], v[8:9]
	s_cbranch_scc0 .LBB0_211
	ds_bpermute_b32 v6, v229, v14
	ds_bpermute_b32 v7, v229, v15
	ds_bpermute_b32 v16, v229, v12
	ds_bpermute_b32 v17, v229, v13
	ds_bpermute_b32 v20, v229, v10
	ds_bpermute_b32 v21, v229, v11
	s_waitcnt lgkmcnt(4)
	v_pk_add_f32 v[6:7], v[14:15], v[6:7]
	ds_bpermute_b32 v14, v230, v6
	s_waitcnt lgkmcnt(3)
	v_pk_add_f32 v[16:17], v[12:13], v[16:17]
	ds_bpermute_b32 v15, v230, v7
	ds_bpermute_b32 v18, v230, v16
	ds_bpermute_b32 v19, v230, v17
	s_waitcnt lgkmcnt(4)
	v_pk_add_f32 v[10:11], v[10:11], v[20:21]
	ds_bpermute_b32 v20, v230, v10
	s_waitcnt lgkmcnt(3)
	v_pk_add_f32 v[6:7], v[6:7], v[14:15]
	ds_bpermute_b32 v21, v230, v11
	s_waitcnt lgkmcnt(2)
	v_pk_add_f32 v[14:15], v[16:17], v[18:19]
	ds_bpermute_b32 v18, v229, v8
	ds_bpermute_b32 v19, v229, v9
	ds_bpermute_b32 v12, v231, v6
	ds_bpermute_b32 v13, v231, v7
	ds_bpermute_b32 v16, v231, v14
	ds_bpermute_b32 v17, v231, v15
	s_waitcnt lgkmcnt(4)
	v_pk_add_f32 v[18:19], v[8:9], v[18:19]
	ds_bpermute_b32 v24, v230, v18
	ds_bpermute_b32 v25, v230, v19
	v_pk_add_f32 v[8:9], v[10:11], v[20:21]
	ds_bpermute_b32 v10, v231, v8
	ds_bpermute_b32 v11, v231, v9
	s_waitcnt lgkmcnt(2)
	v_pk_add_f32 v[18:19], v[18:19], v[24:25]
	ds_bpermute_b32 v20, v231, v18
	ds_bpermute_b32 v21, v231, v19
	s_and_saveexec_b64 s[18:19], s[40:41]
	s_cbranch_execz .LBB0_194
	v_pk_add_f32 v[24:25], v[6:7], v[12:13]
	v_pk_add_f32 v[12:13], v[14:15], v[16:17]
	s_lshl_b32 s30, s100, 6
	s_mov_b32 s4, 0x3b800000
	s_waitcnt lgkmcnt(2)
	v_pk_add_f32 v[6:7], v[8:9], v[10:11]
	s_waitcnt lgkmcnt(0)
	v_pk_add_f32 v[8:9], v[18:19], v[20:21]
	v_lshl_add_u64 v[14:15], s[30:31], 2, v[2:3]
	v_pk_mul_f32 v[12:13], v[12:13], s[4:5] op_sel_hi:[1,0]
	v_pk_mul_f32 v[10:11], v[24:25], s[4:5] op_sel_hi:[1,0]
	v_pk_mul_f32 v[8:9], v[8:9], s[4:5] op_sel_hi:[1,0]
	v_pk_mul_f32 v[6:7], v[6:7], s[4:5] op_sel_hi:[1,0]
	global_store_dwordx4 v[14:15], v[10:13], off
	global_store_dwordx4 v[14:15], v[6:9], off offset:16
	s_branch .LBB0_194
